# P8 ff2 split-K rebalanced stream-K style (2 units of 68 k-tiles per block), proj on all 256 blocks
# speedup vs baseline: 1.0085x; 1.0085x over previous
; #define PG8_STAGE(bufoff, gbase, voff) do { _Pragma("unroll") for (int _i = 0; _i < 2; ++_i) \
;     __builtin_amdgcn_global_load_lds((const unsigned*)((const char*)(gbase) + (voff)[_i]), (PG8_LAS unsigned*)(lds + (bufoff) + ldsw + _i * 8192), 16, 0, 0); } while (0)
; template <bool SEQ>
; DEV bool next_unit(const Gemm& g, int i, int G, int c, Unit& u) {
;   const int nwg = g.nM * g.nN, NSEG = g.nseg;
;   int wgid;
;   if (SEQ) { const int ti = i / NSEG; u.seg = i - ti * NSEG; const long L = (long)ti * G + c; if (L >= nwg) return false; wgid = (int)L; }
;   else { const int L = i * G + c; if (L >= nwg * NSEG) return false; wgid = L / NSEG; u.seg = L - wgid * NSEG; } { const int q = nwg / NXCD, r = nwg % NXCD, xcd = wgid % NXCD, off = wgid / NXCD; wgid = (xcd < r ? xcd * (q + 1) : r * (q + 1) + (xcd - r) * q) + off; }
;   const int nig = WGM * g.nN, gid = wgid / nig, fm = gid * WGM, gsz = (g.nM - fm) < WGM ? (g.nM - fm) : WGM;
;   u.pm = fm + ((wgid % nig) % gsz); u.pn = (wgid % nig) / gsz; return true;
; template <class Epi, bool SEQ>
; DEV void gemm_phase(PG8_LAS unsigned char* lds, const Gemm g, const Epi& E) {
;     ...
;   for (int i = 0; i < 2; ++i) { int R, C; stage_rc(tid * 16 + i * 8192, R, C); const int Rb = Epi::PERM ? ((R & ~31) + perm32(R & 31)) : R;
;     voffA[i] = (unsigned)(R * g.lda + C) * 2u; voffB[i] = (unsigned)(Rb * g.ldb + C) * 2u; }
;   const size_t kstep = (size_t)(BK * 2);
;   const size_t hstepA = (size_t)HALF * g.lda * 2, hstepB = (size_t)HALF * g.ldb * 2;
;   const size_t tstepA = 2 * hstepA, tstepB = 2 * hstepB;
;   const unsigned ldsw = (unsigned)wid * 1024u;
;   const int aoff = lds_byte(wr * 64 + fr, fq * 8), boff = lds_byte(wc * 32 + fr, fq * 8);
;     ...
;   Unit cur, nxt; int ui = 0;
;   if (!next_unit<SEQ>(g, 0, G, cblk, cur)) return;
;   f32x4 acc[2][2][4][2];
; #pragma unroll
;   for (int a = 0; a < 2; ++a)
; #pragma unroll
;     for (int b = 0; b < 2; ++b)
; #pragma unroll
;       for (int m = 0; m < 4; ++m)
; #pragma unroll
;         for (int n = 0; n < 2; ++n) acc[a][b][m][n] = (f32x4){0.f, 0.f, 0.f, 0.f};
;   bf16x8 At[4][2], B0[2][2], B1[2][2];
;   const char* cA = PG8_ABASE(cur); const char* cB = PG8_BBASE(cur);
;   PG8_STAGE(PG8_SB(0, 0), cB, voffB); PG8_STAGE(PG8_SB(0, 1), cB + hstepB, voffB); PG8_STAGE(PG8_SA(0, 0), cA, voffA); PG8_STAGE(PG8_SA(0, 1), cA + hstepA, voffA);
;   if (wr == 1) PG8_BAR;
;   PG8_WAIT_V(2); PG8_BAR;
.LBB0_157:
	v_readlane_b32 s4, v250, 16
	v_mov_b32_e32 v18, v171
	v_readlane_b32 s5, v250, 17
	s_load_dword s3, s[4:5], 0x10
	s_and_b64 s[4:5], s[0:1], exec
	s_mov_b32 s13, 0
	v_readlane_b32 s16, v248, 37
	s_mov_b32 s6, s74
	s_waitcnt lgkmcnt(0)
	s_lshr_b32 s3, s3, 16
	s_cmp_lg_u32 s3, 0
	s_cselect_b64 s[4:5], -1, 0
	s_cmp_lg_u64 s[4:5], 0
	v_readlane_b32 s18, v248, 39
	s_addc_u32 s42, s18, 0
	s_add_i32 s43, s6, s13
	s_cmp_lt_i32 s43, 0
	v_readfirstlane_b32 s12, v18
	v_readlane_b32 s17, v248, 38
	v_readlane_b32 s19, v248, 40
	s_cbranch_scc1 .LBB0_156
	s_and_b64 s[4:5], s[0:1], exec
	s_cselect_b32 s44, 0x44, 64
	s_lshl_b32 s3, s44, 2
	s_xor_b32 s45, s2, 1
	s_lshl_b32 s46, s3, s45
	s_and_b64 s[4:5], s[0:1], exec
	s_cselect_b32 s46, 0x200, s46
	s_cmp_ge_u32 s43, s46
	s_cbranch_scc1 .LBB0_156
	v_lshlrev_b32_e32 v0, 4, v18
	v_add_u32_e32 v1, 0x2000, v0
	v_ashrrev_i32_e32 v2, 31, v1
	v_lshrrev_b32_e32 v2, 22, v2
	v_add_u32_e32 v2, v1, v2
	v_ashrrev_i32_e32 v2, 10, v2
	s_ashr_i32 s15, s12, 8
	v_mul_i32_i24_e32 v3, 0x400, v2
	s_and_b64 s[2:3], s[0:1], exec
	v_sub_u32_e32 v1, v1, v3
	s_mov_b32 s2, 0x100000
	v_lshrrev_b32_e32 v3, 4, v1
	s_cselect_b32 s6, s2, 0x10000
	s_ashr_i32 s14, s12, 6
	v_bitop3_b32 v1, v3, v1, 32 bitop3:0x6c
	s_lshl_b32 s47, s14, 10
	v_ashrrev_i32_e32 v3, 31, v1
	s_and_b64 s[2:3], s[0:1], exec
	v_lshrrev_b32_e32 v3, 26, v3
	s_mov_b32 s2, 0x1a80000
	v_add_u32_e32 v3, v1, v3
	s_cselect_b32 s2, s2, 0x2480000
	v_ashrrev_i32_e32 v4, 6, v3
	v_and_b32_e32 v3, 0xc0, v3
	s_cselect_b32 s48, 0x1000, 0
	s_cselect_b32 s49, s31, s41
	s_cselect_b32 s50, s30, s40
	s_add_u32 s51, s28, s2
	v_sub_u32_e32 v1, v1, v3
	s_addc_u32 s52, s29, 0
	v_ashrrev_i16_sdwa v1, v200, sext(v1) dst_sel:DWORD dst_unused:UNUSED_PAD src0_sel:DWORD src1_sel:BYTE_0
	v_lshlrev_b32_e32 v5, 3, v2
	s_and_b64 s[2:3], s[0:1], exec
	v_bfe_i32 v14, v1, 0, 16
	v_bfe_i32 v1, v18, 27, 1
	v_and_b32_e32 v5, 0x7ffffff0, v5
	s_cselect_b32 s2, 12, 8
	v_lshlrev_b32_e32 v2, 5, v2
	v_lshrrev_b32_e32 v1, 22, v1
	v_add_lshl_u32 v12, v4, v5, s2
	v_and_b32_e32 v13, 32, v2
	v_add_u32_e32 v1, v0, v1
	v_or_b32_e32 v2, v12, v13
	v_and_b32_e32 v1, 0xfffffc00, v1
	v_add_lshl_u32 v128, v2, v14, 1
	v_sub_u32_e32 v0, v0, v1
	v_ashrrev_i32_e32 v2, 31, v18
	v_lshrrev_b32_e32 v1, 4, v0
	v_lshrrev_b32_e32 v2, 26, v2
	v_bitop3_b32 v1, v1, v0, 32 bitop3:0x6c
	v_ashrrev_i32_e32 v0, 31, v0
	v_add_u32_e32 v2, v18, v2
	v_lshrrev_b32_e32 v0, 26, v0
	v_ashrrev_i32_e32 v2, 6, v2
	v_add_u32_e32 v0, v1, v0
	v_lshlrev_b32_e32 v3, 3, v2
	v_ashrrev_i32_e32 v0, 6, v0
	v_and_b32_e32 v3, 0x7ffffff0, v3
	v_add_lshl_u32 v15, v0, v3, s2
	s_lshr_b32 s3, s43, 4
	s_mul_i32 s3, s3, s45
	s_add_i32 s2, s43, s3
	s_mov_b32 s59, 0
	s_lshr_b32 s53, s44, 1
	s_bfe_u32 s3, s2, 0xd0003
	s_and_b32 s2, s2, 7
	s_mul_i32 s2, s53, s2
	s_add_i32 s2, s2, s3
	s_lshr_b32 s3, s2, 2
	s_and_b32 s5, s3, 0xffc
	s_sub_i32 s3, s44, s5
	s_min_i32 s8, s3, 4
	v_mul_i32_i24_e32 v0, 64, v0
	s_and_b32 s9, s2, 15
	s_sext_i32_i8 s2, s8
	v_sub_u32_e32 v0, v1, v0
	v_cvt_f32_i32_e32 v1, s2
	v_lshlrev_b32_e32 v2, 5, v2
	v_and_b32_e32 v16, 32, v2
	v_ashrrev_i16_sdwa v0, v200, sext(v0) dst_sel:DWORD dst_unused:UNUSED_PAD src0_sel:DWORD src1_sel:BYTE_0
	v_or_b32_e32 v2, v15, v16
	v_bfe_i32 v17, v0, 0, 16
	v_add_lshl_u32 v168, v2, v17, 1
	v_rcp_iflag_f32_e32 v2, v1
	v_cvt_f32_ubyte0_e32 v0, s9
	s_ashr_i32 s3, s2, 30
	s_or_b32 s4, s3, 1
	v_mul_f32_e32 v2, v0, v2
	v_trunc_f32_e32 v2, v2
	v_fma_f32 v0, -v2, v1, v0
	v_cvt_i32_f32_e32 v2, v2
	v_cmp_ge_f32_e64 s[2:3], |v0|, |v1|
	s_and_b64 s[2:3], s[2:3], exec
	s_cselect_b32 s2, s4, 0
	v_readfirstlane_b32 s3, v2
	s_add_i32 s2, s3, s2
	s_sext_i32_i8 s4, s2
	s_mul_i32 s2, s2, s8
	s_sub_i32 s2, s9, s2
	s_and_b32 s2, s2, 0xff
	s_add_i32 s8, s5, s2
	s_cmp_eq_u32 s59, 1
	s_cselect_b64 s[2:3], -1, 0
	s_cmp_lg_u32 s59, 0
	s_cselect_b64 s[16:17], -1, 0
	s_and_b64 s[2:3], s[16:17], s[2:3]
	s_and_b32 s18, s43, 15
	s_lshl_b32 s18, s18, 9
	s_mul_i32 s18, s18, s45
	s_and_b64 s[2:3], s[0:1], exec
	s_mov_b32 s9, s7
	s_cselect_b32 s54, 21, 17
	s_lshl_b64 s[2:3], s[8:9], s54
	s_mov_b32 s9, s18
	s_mov_b32 s5, 0
	s_add_u32 s9, s51, s9
	s_addc_u32 s19, s52, s5
	s_ashr_i32 s5, s4, 31
	s_lshl_b64 s[16:17], s[4:5], s54
	s_add_u32 s36, s9, s16
	s_addc_u32 s37, s19, s17
	s_add_i32 s9, s47, 0
	s_add_i32 m0, s9, 0x10000
	v_mov_b32_e32 v129, v169
	global_load_lds_dwordx4 v168, s[36:37]
	s_add_i32 m0, s9, 0x12000
	s_add_u32 s5, s50, s18
	s_addc_u32 s18, s49, 0
	s_add_u32 s16, s36, s6
	global_load_lds_dwordx4 v128, s[36:37]
	s_addc_u32 s17, s37, 0
	s_add_i32 m0, s9, 0x14000
	v_lshl_add_u64 v[0:1], s[36:37], 0, v[168:169]
	global_load_lds_dwordx4 v168, s[16:17]
	s_add_i32 m0, s9, 0x16000
	s_add_u32 s26, s5, s2
	s_addc_u32 s27, s18, s3
	s_add_i32 s55, s9, 0x2000
	global_load_lds_dwordx4 v128, s[16:17]
	s_mov_b32 m0, s9
	s_add_u32 s2, s26, s6
	global_load_lds_dwordx4 v168, s[26:27]
	s_mov_b32 m0, s55
	s_addc_u32 s3, s27, 0
	s_add_i32 s56, s9, 0x4000
	global_load_lds_dwordx4 v128, s[26:27]
	s_mov_b32 m0, s56
	s_add_i32 s57, s9, 0x6000
	global_load_lds_dwordx4 v168, s[2:3]
	s_mov_b32 m0, s57
	s_cmp_eq_u32 s15, 1
	global_load_lds_dwordx4 v128, s[2:3]
	v_lshl_add_u64 v[2:3], s[36:37], 0, v[128:129]
	v_lshl_add_u64 v[4:5], s[16:17], 0, v[168:169]
	v_lshl_add_u64 v[6:7], s[16:17], 0, v[128:129]
	v_lshl_add_u64 v[8:9], s[26:27], 0, v[168:169]
	v_lshl_add_u64 v[10:11], s[26:27], 0, v[128:129]
	s_cselect_b64 s[2:3], -1, 0
	s_cmp_lg_u32 s15, 1
	s_cbranch_scc1 .LBB0_161
	s_barrier
; #define PG8_STAGE(bufoff, gbase, voff) do { _Pragma("unroll") for (int _i = 0; _i < 2; ++_i) \
;     __builtin_amdgcn_global_load_lds((const unsigned*)((const char*)(gbase) + (voff)[_i]), (PG8_LAS unsigned*)(lds + (bufoff) + ldsw + _i * 8192), 16, 0, 0); } while (0)
; #define PG8_WAIT_V(n) asm volatile("s_waitcnt vmcnt(" #n ")" ::: "memory")
; #define PG8_BAR __builtin_amdgcn_s_barrier()
; template <class Epi, bool SEQ>
; DEV void gemm_phase(PG8_LAS unsigned char* lds, const Gemm g, const Epi& E) {
;     ...
;   const int nt = g.K / BK;
;   unsigned voffA[2], voffB[2];
; #pragma unroll
;   for (int i = 0; i < 2; ++i) { int R, C; stage_rc(tid * 16 + i * 8192, R, C); const int Rb = Epi::PERM ? ((R & ~31) + perm32(R & 31)) : R;
;     voffA[i] = (unsigned)(R * g.lda + C) * 2u; voffB[i] = (unsigned)(Rb * g.ldb + C) * 2u; }
;   const size_t kstep = (size_t)(BK * 2);
;   const size_t hstepA = (size_t)HALF * g.lda * 2, hstepB = (size_t)HALF * g.ldb * 2;
;   const size_t tstepA = 2 * hstepA, tstepB = 2 * hstepB;
;   const unsigned ldsw = (unsigned)wid * 1024u;
;   const int aoff = lds_byte(wr * 64 + fr, fq * 8), boff = lds_byte(wc * 32 + fr, fq * 8);
;     ...
;   Unit cur, nxt; int ui = 0;
;   if (!next_unit<SEQ>(g, 0, G, cblk, cur)) return;
;   f32x4 acc[2][2][4][2];
; #pragma unroll
;   for (int a = 0; a < 2; ++a)
; #pragma unroll
;     for (int b = 0; b < 2; ++b)
; #pragma unroll
;       for (int m = 0; m < 4; ++m)
; #pragma unroll
;         for (int n = 0; n < 2; ++n) acc[a][b][m][n] = (f32x4){0.f, 0.f, 0.f, 0.f};
;   bf16x8 At[4][2], B0[2][2], B1[2][2];
;   const char* cA = PG8_ABASE(cur); const char* cB = PG8_BBASE(cur);
;   PG8_STAGE(PG8_SB(0, 0), cB, voffB); PG8_STAGE(PG8_SB(0, 1), cB + hstepB, voffB); PG8_STAGE(PG8_SA(0, 0), cA, voffA); PG8_STAGE(PG8_SA(0, 1), cA + hstepA, voffA);
;   if (wr == 1) PG8_BAR;
;   PG8_WAIT_V(2); PG8_BAR;
;   PG8_STAGE(PG8_SB(1, 0), cB + kstep, voffB); PG8_STAGE(PG8_SA(1, 0), cA + kstep, voffA); PG8_STAGE(PG8_SB(1, 1), cB + hstepB + kstep, voffB);
;   PG8_WAIT_V(6); PG8_BAR;
.LBB0_161:
	v_bfe_u32 v19, v18, 4, 2
	v_and_b32_e32 v20, 15, v18
	s_and_b32 s58, s43, 15
	s_lshl_b32 s58, s58, 2
	s_sub_i32 s58, 64, s58
	s_and_b64 s[16:17], s[0:1], exec
	v_lshlrev_b32_e32 v21, 4, v19
	v_lshlrev_b32_e32 v18, 2, v18
	s_cselect_b32 s58, s58, 4
	v_lshl_or_b32 v134, s15, 6, v20
	v_lshl_or_b32 v20, v20, 6, v21
	s_lshl_b32 s5, s15, 13
	v_and_b32_e32 v18, 32, v18
	v_bitop3_b32 v21, v20, s5, v18 bitop3:0xde
	s_lshl_b32 s5, s14, 5
	s_and_b32 s5, s5, 0x60
	s_lshl_b32 s14, s5, 7
	v_bitop3_b32 v135, v20, s14, v18 bitop3:0xde
	s_and_b64 s[14:15], s[0:1], exec
	s_mov_b32 s14, 0x8800000
	s_cselect_b32 s14, s14, 0xaa00000
	s_cselect_b32 s61, 2, 1
	s_add_u32 s62, s30, s14
	s_addc_u32 s63, s31, 0
	s_add_i32 m0, s9, 0x18000
	v_lshl_add_u64 v[0:1], v[0:1], 0, s[10:11]
	s_waitcnt vmcnt(2)
	s_barrier
	global_load_lds_dwordx4 v[0:1], off
	v_lshl_add_u64 v[0:1], v[2:3], 0, s[10:11]
	s_add_i32 m0, s9, 0x1a000
	s_add_i32 s65, s9, 0x8000
	global_load_lds_dwordx4 v[0:1], off
	v_lshl_add_u64 v[0:1], v[8:9], 0, s[10:11]
	s_mov_b32 m0, s65
	s_add_i32 s66, s9, 0xa000
	global_load_lds_dwordx4 v[0:1], off
	v_lshl_add_u64 v[0:1], v[10:11], 0, s[10:11]
	s_mov_b32 m0, s66
	s_add_i32 s64, s42, s13
	global_load_lds_dwordx4 v[0:1], off
	s_add_i32 m0, s9, 0x1c000
	v_lshl_add_u64 v[0:1], v[4:5], 0, s[10:11]
	global_load_lds_dwordx4 v[0:1], off
	v_lshl_add_u64 v[0:1], v[6:7], 0, s[10:11]
	s_add_i32 m0, s9, 0x1e000
	s_add_i32 s67, s58, -2
	global_load_lds_dwordx4 v[0:1], off
	v_cvt_f32_ubyte0_e32 v0, s61
	v_rcp_iflag_f32_e32 v0, v0
	s_cmpk_lt_u32 s12, 0x100
	s_cselect_b64 s[12:13], -1, 0
	v_lshl_or_b32 v136, v19, 2, s5
	v_mul_f32_e32 v0, 0x4f7ffffe, v0
	v_cvt_u32_f32_e32 v0, v0
	s_sub_i32 s5, 0, s61
	v_mov_b32_e32 v1, v169
	s_waitcnt vmcnt(6)
	v_readfirstlane_b32 s14, v0
	v_add_u32_e32 v0, v15, v16
	v_add_lshl_u32 v0, v0, v17, 1
	s_mul_i32 s5, s5, s14
	v_lshl_add_u64 v[130:131], s[6:7], 0, v[0:1]
	v_add_u32_e32 v0, v12, v13
	s_mul_hi_u32 s5, s14, s5
	v_add_lshl_u32 v0, v0, v14, 1
	s_mov_b32 s60, 0
	s_add_i32 s68, s14, s5
	v_lshl_add_u64 v[132:133], s[6:7], 0, v[0:1]
	v_add_u32_e32 v137, 0, v21
	s_barrier
	s_branch .LBB0_164

; template <bool SEQ>
; DEV bool next_unit(const Gemm& g, int i, int G, int c, Unit& u) {
;   const int nwg = g.nM * g.nN, NSEG = g.nseg;
;   int wgid;
;   if (SEQ) { const int ti = i / NSEG; u.seg = i - ti * NSEG; const long L = (long)ti * G + c; if (L >= nwg) return false; wgid = (int)L; }
;   else { const int L = i * G + c; if (L >= nwg * NSEG) return false; wgid = L / NSEG; u.seg = L - wgid * NSEG; } { const int q = nwg / NXCD, r = nwg % NXCD, xcd = wgid % NXCD, off = wgid / NXCD; wgid = (xcd < r ? xcd * (q + 1) : r * (q + 1) + (xcd - r) * q) + off; }
;   const int nig = WGM * g.nN, gid = wgid / nig, fm = gid * WGM, gsz = (g.nM - fm) < WGM ? (g.nM - fm) : WGM;
;   u.pm = fm + ((wgid % nig) % gsz); u.pn = (wgid % nig) / gsz; return true;
; template <class Epi, bool SEQ>
; DEV void gemm_phase(PG8_LAS unsigned char* lds, const Gemm g, const Epi& E) {
;     ...
;     const bool has_next = next_unit<SEQ>(g, ui + 1, G, cblk, nxt);
;     const char* nA = has_next ? PG8_ABASE(nxt) : cA; const char* nB = has_next ? PG8_BBASE(nxt) : cB;
.LBB0_163:
	s_andn2_b64 vcc, exec, s[4:5]
	s_mov_b32 s59, s69
	s_mov_b32 s4, s14
	s_mov_b32 s8, s16
	s_mov_b64 s[36:37], s[20:21]
	s_mov_b64 s[26:27], s[18:19]
	s_and_b32 s58, s43, 15
	s_lshl_b32 s58, s58, 2
	s_add_i32 s58, s58, 4
	s_add_i32 s67, s58, -2
	s_cbranch_vccz .LBB0_155
.LBB0_164:
	s_add_i32 s60, s60, 1
	s_mul_i32 s5, s60, s64
	s_add_i32 s5, s5, s43
	s_cmp_lt_i32 s5, s46
	s_cselect_b64 s[18:19], -1, 0
	s_cmp_ge_i32 s5, s46
	s_cbranch_scc1 .LBB0_166
	s_lshr_b32 s14, s43, 4
	s_add_i32 s14, s14, s43
	s_add_i32 s14, s14, 1
	s_ashr_i32 s15, s14, 31
	s_lshr_b32 s15, s15, 29
	s_add_i32 s15, s14, s15
	s_ashr_i32 s16, s15, 3
	s_and_b32 s15, s15, -8
	s_sub_i32 s15, s14, s15
	s_lshr_b32 s17, s15, 31
	s_or_b32 s17, s17, s53
	s_mul_i32 s15, s17, s15
	s_add_i32 s15, s15, s16
	s_ashr_i32 s16, s15, 31
	s_lshr_b32 s16, s16, 28
	s_add_i32 s16, s15, s16
	s_ashr_i32 s17, s16, 4
	s_lshl_b32 s17, s17, 2
	s_sub_i32 s20, s44, s17
	s_min_i32 s20, s20, 4
	s_abs_i32 s21, s20
	v_cvt_f32_u32_e32 v0, s21
	s_mov_b32 s69, 1
	s_and_b32 s5, s16, -16
	v_rcp_iflag_f32_e32 v0, v0
	s_sub_i32 s16, 0, s21
	s_sub_i32 s5, s15, s5
	s_abs_i32 s15, s5
	v_mul_f32_e32 v0, 0x4f7ffffe, v0
	v_cvt_u32_f32_e32 v0, v0
	s_xor_b32 s14, s5, s20
	s_ashr_i32 s14, s14, 31
	v_readfirstlane_b32 s38, v0
	s_mul_i32 s16, s16, s38
	s_mul_hi_u32 s16, s38, s16
	s_add_i32 s38, s38, s16
	s_mul_hi_u32 s16, s15, s38
	s_mul_i32 s38, s16, s21
	s_sub_i32 s15, s15, s38
	s_add_i32 s38, s16, 1
	s_sub_i32 s39, s15, s21
	s_cmp_ge_u32 s15, s21
	s_cselect_b32 s16, s38, s16
	s_cselect_b32 s15, s39, s15
	s_add_i32 s38, s16, 1
	s_cmp_ge_u32 s15, s21
	s_cselect_b32 s15, s38, s16
	s_xor_b32 s15, s15, s14
	s_sub_i32 s14, s15, s14
	s_mul_i32 s15, s14, s20
	s_sub_i32 s5, s5, s15
	s_add_i32 s16, s17, s5
.LBB0_166:
	v_cndmask_b32_e64 v0, 0, 1, s[18:19]
	v_cmp_ne_u32_e64 s[38:39], 1, v0
	s_andn2_b64 vcc, exec, s[18:19]
	s_mov_b64 s[18:19], s[26:27]
	s_cbranch_vccnz .LBB0_168
	s_cmp_eq_u32 s69, 1
	s_cselect_b64 s[18:19], -1, 0
	s_cmp_lg_u32 s69, 0
	s_cselect_b64 s[20:21], -1, 0
	s_and_b64 s[18:19], s[20:21], s[18:19]
	s_and_b64 s[18:19], s[18:19], exec
	s_mov_b32 s5, 0
	s_add_u32 s5, s50, s5
	s_addc_u32 s15, s49, 0
	s_ashr_i32 s17, s16, 31
	s_lshl_b64 s[18:19], s[16:17], s54
	s_add_u32 s18, s5, s18
	s_addc_u32 s19, s15, s19
.LBB0_168:
	s_and_b64 vcc, exec, s[38:39]
	s_mov_b64 s[20:21], s[36:37]
	s_cbranch_vccnz .LBB0_170
	s_mov_b32 s15, 0
	s_mov_b32 s5, 0
	s_add_u32 s17, s51, s15
	s_addc_u32 s5, s52, s5
	s_ashr_i32 s15, s14, 31
	s_lshl_b64 s[20:21], s[14:15], s54
	s_add_u32 s20, s17, s20
	s_addc_u32 s21, s5, s21

; DEV unsigned cvt_pk_bf16(float lo, float hi) { const f32x2_ v = {lo, hi}; return __builtin_bit_cast(unsigned, __builtin_convertvector(v, bf16x2n_)); }
;   DEV void operator()(const f32x4 (&acc)[2][2][4][2], const Unit& u, int wr, int wc, int fr, int fq) const {
;     const int row0 = u.pm * BM + wr * 64 + fr, col0 = u.pn * BM + wc * 32 + 4 * fq;
; #pragma unroll
;     for (int ai = 0; ai < 2; ++ai)
; #pragma unroll
;       for (int m = 0; m < 4; ++m) {
;         const size_t ro = (size_t)(row0 + ai * HALF + m * 16) * D + col0;
; #pragma unroll
;         for (int bj = 0; bj < 2; ++bj)
; #pragma unroll
;           for (int n = 0; n < 2; ++n) {
;             const f32x4 v = acc[ai][bj][m][n];
;             u32x2 w; w.x = cvt_pk_bf16(v[0], v[1]); w.y = cvt_pk_bf16(v[2], v[3]);
;             *(u32x2*)((u.seg == 0 ? C0 : C1) + ro + bj * HALF + n * 16) = w;
;           }
;       }
;   }
.LBB0_174:
	v_lshl_add_u32 v140, s8, 8, v134
	v_lshl_or_b32 v138, s4, 8, v136
	v_ashrrev_i32_e32 v141, 31, v140
	s_cmp_eq_u32 s59, 0
	v_ashrrev_i32_e32 v139, 31, v138
	v_lshlrev_b64 v[142:143], 11, v[140:141]
	s_cselect_b32 s5, s63, s25
	s_cselect_b32 s4, s62, s24
	v_cvt_pk_bf16_f32 v124, v124, v125
	v_cvt_pk_bf16_f32 v125, v126, v127
	v_lshl_add_u64 v[126:127], s[4:5], 0, v[142:143]
	v_lshlrev_b64 v[138:139], 1, v[138:139]
	v_lshl_add_u64 v[126:127], v[126:127], 0, v[138:139]
	v_cvt_pk_bf16_f32 v104, v104, v105
	v_cvt_pk_bf16_f32 v105, v106, v107
	global_store_dwordx2 v[126:127], v[104:105], off offset:288
	v_or_b32_e32 v104, 16, v140
	v_ashrrev_i32_e32 v105, 31, v104
	v_lshlrev_b64 v[104:105], 11, v[104:105]
	v_lshl_add_u64 v[104:105], s[4:5], 0, v[104:105]
	v_lshl_add_u64 v[104:105], v[104:105], 0, v[138:139]
	v_cvt_pk_bf16_f32 v88, v88, v89
	v_cvt_pk_bf16_f32 v89, v90, v91
	global_store_dwordx2 v[104:105], v[88:89], off offset:288
	v_or_b32_e32 v88, 32, v140
	v_ashrrev_i32_e32 v89, 31, v88
	v_lshlrev_b64 v[88:89], 11, v[88:89]
	v_lshl_add_u64 v[88:89], s[4:5], 0, v[88:89]
	v_lshl_add_u64 v[88:89], v[88:89], 0, v[138:139]
	v_cvt_pk_bf16_f32 v72, v72, v73
	v_cvt_pk_bf16_f32 v73, v74, v75
	global_store_dwordx2 v[88:89], v[72:73], off offset:288
	v_or_b32_e32 v72, 48, v140
	v_ashrrev_i32_e32 v73, 31, v72
	v_lshlrev_b64 v[72:73], 11, v[72:73]
	v_lshl_add_u64 v[72:73], s[4:5], 0, v[72:73]
	v_lshl_add_u64 v[72:73], v[72:73], 0, v[138:139]
	v_cvt_pk_bf16_f32 v64, v64, v65
	v_cvt_pk_bf16_f32 v65, v66, v67
	global_store_dwordx2 v[72:73], v[64:65], off offset:288
	s_mov_b64 s[4:5], 0x40000
	v_add_co_u32_e32 v64, vcc, s92, v126
	v_cvt_pk_bf16_f32 v60, v60, v61
	v_cvt_pk_bf16_f32 v61, v62, v63
	v_lshl_add_u64 v[62:63], v[126:127], 0, s[4:5]
	v_addc_co_u32_e32 v65, vcc, 0, v127, vcc
	v_cvt_pk_bf16_f32 v48, v48, v49
	v_cvt_pk_bf16_f32 v49, v50, v51
	global_store_dwordx2 v[62:63], v[48:49], off offset:256
	s_mov_b64 s[4:5], 0x48000
	v_add_co_u32_e32 v48, vcc, s93, v126
	v_cvt_pk_bf16_f32 v40, v40, v41
	v_cvt_pk_bf16_f32 v41, v42, v43
	v_lshl_add_u64 v[42:43], v[126:127], 0, s[4:5]
	v_addc_co_u32_e32 v49, vcc, 0, v127, vcc
	v_cvt_pk_bf16_f32 v32, v32, v33
	v_cvt_pk_bf16_f32 v33, v34, v35
	global_store_dwordx2 v[42:43], v[32:33], off offset:256
	s_mov_b64 s[4:5], 0x50000
	v_add_co_u32_e32 v32, vcc, s96, v126
	v_cvt_pk_bf16_f32 v24, v24, v25
	v_cvt_pk_bf16_f32 v25, v26, v27
	v_lshl_add_u64 v[26:27], v[126:127], 0, s[4:5]
	v_addc_co_u32_e32 v33, vcc, 0, v127, vcc
	v_cvt_pk_bf16_f32 v16, v16, v17
	v_cvt_pk_bf16_f32 v17, v18, v19
	global_store_dwordx2 v[26:27], v[16:17], off offset:256
	v_cvt_pk_bf16_f32 v8, v8, v9
	v_cvt_pk_bf16_f32 v9, v10, v11
	v_add_co_u32_e32 v16, vcc, s97, v126
	v_cvt_pk_bf16_f32 v106, v116, v117
	v_cvt_pk_bf16_f32 v107, v118, v119
	v_cvt_pk_bf16_f32 v90, v100, v101
	v_cvt_pk_bf16_f32 v91, v102, v103
	v_cvt_pk_bf16_f32 v74, v84, v85
	v_cvt_pk_bf16_f32 v75, v86, v87
	global_store_dwordx2 v[62:63], v[40:41], off offset:288
	v_cvt_pk_bf16_f32 v40, v52, v53
	v_cvt_pk_bf16_f32 v41, v54, v55
	global_store_dwordx2 v[42:43], v[24:25], off offset:288
	v_cvt_pk_bf16_f32 v24, v36, v37
	v_cvt_pk_bf16_f32 v25, v38, v39
	global_store_dwordx2 v[26:27], v[8:9], off offset:288
	v_cvt_pk_bf16_f32 v8, v20, v21
	v_cvt_pk_bf16_f32 v9, v22, v23
	s_mov_b64 s[4:5], 0x58000
	v_addc_co_u32_e32 v17, vcc, 0, v127, vcc
	v_cvt_pk_bf16_f32 v120, v120, v121
	v_cvt_pk_bf16_f32 v121, v122, v123
	v_cvt_pk_bf16_f32 v112, v112, v113
	v_cvt_pk_bf16_f32 v113, v114, v115
	global_store_dwordx2 v[104:105], v[106:107], off
	v_cvt_pk_bf16_f32 v106, v108, v109
	v_cvt_pk_bf16_f32 v107, v110, v111
	v_cvt_pk_bf16_f32 v96, v96, v97
	v_cvt_pk_bf16_f32 v97, v98, v99
	global_store_dwordx2 v[88:89], v[90:91], off
	v_cvt_pk_bf16_f32 v90, v92, v93
	v_cvt_pk_bf16_f32 v91, v94, v95
	v_cvt_pk_bf16_f32 v80, v80, v81
	v_cvt_pk_bf16_f32 v81, v82, v83
	global_store_dwordx2 v[72:73], v[74:75], off
	v_cvt_pk_bf16_f32 v74, v76, v77
	v_cvt_pk_bf16_f32 v75, v78, v79
	v_cvt_pk_bf16_f32 v68, v68, v69
	v_cvt_pk_bf16_f32 v69, v70, v71
	v_cvt_pk_bf16_f32 v56, v56, v57
	v_cvt_pk_bf16_f32 v57, v58, v59
	global_store_dwordx2 v[48:49], v[40:41], off
	v_cvt_pk_bf16_f32 v40, v44, v45
	v_cvt_pk_bf16_f32 v41, v46, v47
	global_store_dwordx2 v[32:33], v[24:25], off
	v_cvt_pk_bf16_f32 v24, v28, v29
	v_cvt_pk_bf16_f32 v25, v30, v31
	v_lshl_add_u64 v[10:11], v[126:127], 0, s[4:5]
	global_store_dwordx2 v[16:17], v[8:9], off
	v_cvt_pk_bf16_f32 v8, v12, v13
	v_cvt_pk_bf16_f32 v9, v14, v15
	v_cvt_pk_bf16_f32 v4, v4, v5
	v_cvt_pk_bf16_f32 v5, v6, v7
	v_cvt_pk_bf16_f32 v0, v0, v1
	v_cvt_pk_bf16_f32 v1, v2, v3
	s_and_b64 vcc, exec, s[38:39]
	s_mov_b64 s[4:5], -1
	global_store_dwordx2 v[126:127], v[124:125], off
	global_store_dwordx2 v[126:127], v[120:121], off offset:32
	global_store_dwordx2 v[126:127], v[112:113], off offset:256
	global_store_dwordx2 v[104:105], v[106:107], off offset:32
	global_store_dwordx2 v[104:105], v[96:97], off offset:256
	global_store_dwordx2 v[88:89], v[90:91], off offset:32
	global_store_dwordx2 v[88:89], v[80:81], off offset:256
	global_store_dwordx2 v[72:73], v[74:75], off offset:32
	global_store_dwordx2 v[72:73], v[68:69], off offset:256
	global_store_dwordx2 v[64:65], v[60:61], off
	global_store_dwordx2 v[62:63], v[56:57], off offset:32
	global_store_dwordx2 v[42:43], v[40:41], off offset:32
	global_store_dwordx2 v[26:27], v[24:25], off offset:32
	global_store_dwordx2 v[10:11], v[8:9], off offset:32
	global_store_dwordx2 v[10:11], v[4:5], off offset:256
	global_store_dwordx2 v[10:11], v[0:1], off offset:288
	s_cmp_lg_u32 s58, 64
	s_cbranch_scc1 .Lp8_zf_skip
; DEV unsigned cvt_pk_bf16(float lo, float hi) { const f32x2_ v = {lo, hi}; return __builtin_bit_cast(unsigned, __builtin_convertvector(v, bf16x2n_)); }
; #define PG8_BAR __builtin_amdgcn_s_barrier()
; template <class Epi, bool SEQ>
; DEV void gemm_phase(PG8_LAS unsigned char* lds, const Gemm g, const Epi& E) {
;     ...
;     if (!has_next) break;
;     if (!keep) {
; #pragma unroll
;       for (int a = 0; a < 2; ++a)
; #pragma unroll
;         for (int b = 0; b < 2; ++b)
; #pragma unroll
;           for (int m = 0; m < 4; ++m)
; #pragma unroll
;             for (int n = 0; n < 2; ++n) acc[a][b][m][n] = (f32x4){0.f, 0.f, 0.f, 0.f};
;     }
;     cur = nxt; cA = nA; cB = nB; ++ui;
;     if (wr == 1) PG8_BAR;
;   DEV void operator()(const f32x4 (&acc)[2][2][4][2], const Unit& u, int wr, int wc, int fr, int fq) const {
;     ...
;         for (int bj = 0; bj < 2; ++bj)
; #pragma unroll
;           for (int n = 0; n < 2; ++n) {
;             const f32x4 v = acc[ai][bj][m][n];
;             u32x2 w; w.x = cvt_pk_bf16(v[0], v[1]); w.y = cvt_pk_bf16(v[2], v[3]);
;             *(u32x2*)((u.seg == 0 ? C0 : C1) + ro + bj * HALF + n * 16) = w;
;           }
	s_cmp_eq_u32 s59, 0
	s_cselect_b32 s22, s24, s62
	s_cselect_b32 s23, s25, s63
	s_cselect_b32 s34, s62, s24
	s_cselect_b32 s35, s63, s25
	s_sub_u32 s22, s22, s34
	s_subb_u32 s23, s23, s35
	v_mov_b32_e32 v2, 0
	v_mov_b32_e32 v3, 0
	v_lshl_add_u64 v[126:127], v[126:127], 0, s[22:23]
	v_lshl_add_u64 v[104:105], v[104:105], 0, s[22:23]
	v_lshl_add_u64 v[88:89], v[88:89], 0, s[22:23]
	v_lshl_add_u64 v[72:73], v[72:73], 0, s[22:23]
	v_lshl_add_u64 v[62:63], v[62:63], 0, s[22:23]
	v_lshl_add_u64 v[42:43], v[42:43], 0, s[22:23]
	v_lshl_add_u64 v[26:27], v[26:27], 0, s[22:23]
	v_lshl_add_u64 v[48:49], v[48:49], 0, s[22:23]
	v_lshl_add_u64 v[32:33], v[32:33], 0, s[22:23]
	v_lshl_add_u64 v[16:17], v[16:17], 0, s[22:23]
	v_lshl_add_u64 v[64:65], v[64:65], 0, s[22:23]
	v_lshl_add_u64 v[10:11], v[10:11], 0, s[22:23]
	global_store_dwordx2 v[126:127], v[2:3], off offset:288
	global_store_dwordx2 v[104:105], v[2:3], off offset:288
	global_store_dwordx2 v[88:89], v[2:3], off offset:288
	global_store_dwordx2 v[72:73], v[2:3], off offset:288
	global_store_dwordx2 v[62:63], v[2:3], off offset:256
	global_store_dwordx2 v[42:43], v[2:3], off offset:256
	global_store_dwordx2 v[26:27], v[2:3], off offset:256
	global_store_dwordx2 v[62:63], v[2:3], off offset:288
	global_store_dwordx2 v[42:43], v[2:3], off offset:288
	global_store_dwordx2 v[26:27], v[2:3], off offset:288
	global_store_dwordx2 v[104:105], v[2:3], off
	global_store_dwordx2 v[88:89], v[2:3], off
	global_store_dwordx2 v[72:73], v[2:3], off
	global_store_dwordx2 v[48:49], v[2:3], off
	global_store_dwordx2 v[32:33], v[2:3], off
	global_store_dwordx2 v[16:17], v[2:3], off
	global_store_dwordx2 v[126:127], v[2:3], off
	global_store_dwordx2 v[126:127], v[2:3], off offset:32
	global_store_dwordx2 v[126:127], v[2:3], off offset:256
	global_store_dwordx2 v[104:105], v[2:3], off offset:32
	global_store_dwordx2 v[104:105], v[2:3], off offset:256
	global_store_dwordx2 v[88:89], v[2:3], off offset:32
	global_store_dwordx2 v[88:89], v[2:3], off offset:256
	global_store_dwordx2 v[72:73], v[2:3], off offset:32
	global_store_dwordx2 v[72:73], v[2:3], off offset:256
	global_store_dwordx2 v[64:65], v[2:3], off
	global_store_dwordx2 v[62:63], v[2:3], off offset:32
	global_store_dwordx2 v[42:43], v[2:3], off offset:32
	global_store_dwordx2 v[26:27], v[2:3], off offset:32
	global_store_dwordx2 v[10:11], v[2:3], off offset:32
	global_store_dwordx2 v[10:11], v[2:3], off offset:256
	global_store_dwordx2 v[10:11], v[2:3], off offset:288
.Lp8_zf_skip:
	s_cbranch_vccnz .LBB0_163
	s_andn2_b64 vcc, exec, s[2:3]
	s_cbranch_vccnz .LBB0_162
	s_barrier
	s_branch .LBB0_162
